# baseline (speedup 1.0000x reference)
; #define WAIT_V0() asm volatile("s_waitcnt vmcnt(0)" ::: "memory")
; #define WAIT_L0() asm volatile("s_waitcnt lgkmcnt(0)" ::: "memory")
; __device__ __forceinline__ void ph_indexer(const Params& p, char* shm) {
;     ...
;       for (int st = 0; st < nst; ++st) {
;         if (st == 0) WAIT_V0(); else asm volatile("s_waitcnt vmcnt(4)" ::: "memory");
;         WAIT_L0();
;         __builtin_amdgcn_s_barrier();
;         if (st + 1 < nst) IDX_STAGE((st + 1) & 1, st + 1);
.LBB0_920:
	s_cmp_eq_u32 s4, 0
	s_cselect_b64 s[20:21], -1, 0
	s_cmp_lg_u32 s4, 0
	s_mov_b64 s[22:23], -1
	s_cbranch_scc0 .LBB0_922
	s_waitcnt vmcnt(2)
	s_mov_b64 s[22:23], 0

; __device__ __forceinline__ void ph_indexer(const Params& p, char* shm) {
;     ...
;           IDX_TILE(ktp * 2, pr0);
;           __builtin_amdgcn_sched_barrier(0);
;           IDX_TILE(ktp * 2 + 1, pr1);
;           __builtin_amdgcn_sched_barrier(0);
;     ...
; #pragma unroll
;           for (int q = 0; q < 2; ++q) {
;             const float mine = half ? pr1[q] : pr0[q];
;             const float send = half ? pr0[q] : pr1[q];
;             const float recv = __shfl_xor(send, 32);
;             p.SC[(rowb + wid * 2 + q) * L + st * 128 + ktp * 64 + lane] = mine + recv;
;           }
.LBB0_928:
	s_lshl_b32 s3, s4, 15
	v_cmp_lt_i32_e32 vcc, v209, v208
	s_and_b32 s3, s3, 0x8000
	s_lshl_b32 s4, s4, 7
	v_cndmask_b32_e32 v0, v207, v209, vcc
	v_or_b32_e32 v129, s3, v117
	v_lshlrev_b32_e32 v119, 2, v0
	v_lshl_add_u64 v[138:139], s[4:5], 2, v[124:125]
	ds_read_b128 v[172:175], v129
	ds_read_b128 v[176:179], v129 offset:256
	ds_read_b128 v[180:183], v129 offset:2048
	ds_read_b128 v[184:187], v129 offset:2304
	ds_read_b128 v[188:191], v129 offset:4096
	ds_read_b128 v[192:195], v129 offset:4352
	ds_read_b128 v[196:199], v129 offset:6144
	ds_read_b128 v[226:229], v129 offset:6400
	s_waitcnt lgkmcnt(8)
	v_cvt_f32_f16_e32 v140, v34
	v_cvt_f32_f16_sdwa v141, v34 dst_sel:DWORD dst_unused:UNUSED_PAD src0_sel:WORD_1
	v_cvt_f32_f16_e32 v142, v35
	v_cvt_f32_f16_sdwa v143, v35 dst_sel:DWORD dst_unused:UNUSED_PAD src0_sel:WORD_1
	v_cvt_f32_f16_e32 v144, v36
	v_cvt_f32_f16_sdwa v145, v36 dst_sel:DWORD dst_unused:UNUSED_PAD src0_sel:WORD_1
	v_cvt_f32_f16_e32 v146, v37
	v_cvt_f32_f16_sdwa v147, v37 dst_sel:DWORD dst_unused:UNUSED_PAD src0_sel:WORD_1
	v_cvt_f32_f16_e32 v148, v38
	v_cvt_f32_f16_sdwa v149, v38 dst_sel:DWORD dst_unused:UNUSED_PAD src0_sel:WORD_1
	v_cvt_f32_f16_e32 v150, v39
	v_cvt_f32_f16_sdwa v151, v39 dst_sel:DWORD dst_unused:UNUSED_PAD src0_sel:WORD_1
	v_cvt_f32_f16_e32 v152, v40
	v_cvt_f32_f16_sdwa v153, v40 dst_sel:DWORD dst_unused:UNUSED_PAD src0_sel:WORD_1
	v_cvt_f32_f16_e32 v154, v41
	v_cvt_f32_f16_sdwa v155, v41 dst_sel:DWORD dst_unused:UNUSED_PAD src0_sel:WORD_1
	s_cmp_eq_u32 s22, 1
	s_cbranch_scc1 .Lidx_first_s0
	s_waitcnt lgkmcnt(7)
	v_mfma_f32_16x16x32_bf16 v[0:3], v[74:77], v[172:175], 0
	v_max_i32_e32 v230, 0, v16
	v_fma_f32 v220, v230, v148, 0
	v_max_i32_e32 v231, 0, v17
	v_mfma_f32_16x16x32_bf16 v[8:11], v[62:65], v[172:175], 0
	v_fmac_f32_e32 v220, v231, v149
	v_max_i32_e32 v230, 0, v18
	v_fmac_f32_e32 v220, v230, v150
	s_waitcnt lgkmcnt(6)
	v_mfma_f32_16x16x32_bf16 v[4:7], v[74:77], v[176:179], 0
	v_max_i32_e32 v231, 0, v19
	v_fmac_f32_e32 v220, v231, v151
	v_max_i32_e32 v230, 0, v24
	v_mfma_f32_16x16x32_bf16 v[12:15], v[62:65], v[176:179], 0
	v_fmac_f32_e32 v220, v230, v152
	v_max_i32_e32 v231, 0, v25
	v_fmac_f32_e32 v220, v231, v153
	s_waitcnt lgkmcnt(5)
	v_mfma_f32_16x16x32_bf16 v[0:3], v[50:53], v[180:183], v[0:3]
	v_max_i32_e32 v230, 0, v26
	v_fmac_f32_e32 v220, v230, v154
	v_max_i32_e32 v231, 0, v27
	v_mfma_f32_16x16x32_bf16 v[8:11], v[66:69], v[180:183], v[8:11]
	v_fmac_f32_e32 v220, v231, v155
	v_max_i32_e32 v230, 0, v20
	v_fma_f32 v221, v230, v148, 0
	s_waitcnt lgkmcnt(4)
	v_mfma_f32_16x16x32_bf16 v[4:7], v[50:53], v[184:187], v[4:7]
	v_max_i32_e32 v231, 0, v21
	v_fmac_f32_e32 v221, v231, v149
	v_max_i32_e32 v230, 0, v22
	v_mfma_f32_16x16x32_bf16 v[12:15], v[66:69], v[184:187], v[12:15]
	v_fmac_f32_e32 v221, v230, v150
	v_max_i32_e32 v231, 0, v23
	v_fmac_f32_e32 v221, v231, v151
	s_waitcnt lgkmcnt(3)
	v_mfma_f32_16x16x32_bf16 v[0:3], v[54:57], v[188:191], v[0:3]
	v_max_i32_e32 v230, 0, v28
	v_fmac_f32_e32 v221, v230, v152
	v_max_i32_e32 v231, 0, v29
	v_mfma_f32_16x16x32_bf16 v[8:11], v[70:73], v[188:191], v[8:11]
	v_fmac_f32_e32 v221, v231, v153
	v_max_i32_e32 v230, 0, v30
	v_fmac_f32_e32 v221, v230, v154
	s_waitcnt lgkmcnt(2)
	v_mfma_f32_16x16x32_bf16 v[4:7], v[54:57], v[192:195], v[4:7]
	v_max_i32_e32 v231, 0, v31
	v_fmac_f32_e32 v221, v231, v155
	s_nop 1
	v_mfma_f32_16x16x32_bf16 v[12:15], v[70:73], v[192:195], v[12:15]
	v_permlane16_swap_b32_e32 v222, v223
	v_permlane16_swap_b32_e32 v218, v219
	v_permlane16_swap_b32_e32 v202, v203
	s_waitcnt lgkmcnt(1)
	v_mfma_f32_16x16x32_bf16 v[0:3], v[58:61], v[196:199], v[0:3]
	v_permlane16_swap_b32_e32 v220, v221
	v_add_f32_e32 v222, v222, v223
	v_add_f32_e32 v218, v218, v219
	v_mfma_f32_16x16x32_bf16 v[8:11], v[78:81], v[196:199], v[8:11]
	v_add_f32_e32 v202, v202, v203
	v_add_f32_e32 v220, v220, v221
	s_nop 1
	s_waitcnt lgkmcnt(0)
	v_mfma_f32_16x16x32_bf16 v[4:7], v[58:61], v[226:229], v[4:7]
	v_permlane32_swap_b32_e32 v222, v218
	v_permlane32_swap_b32_e32 v202, v220
	v_add_f32_e32 v222, v222, v218
	v_mfma_f32_16x16x32_bf16 v[12:15], v[78:81], v[226:229], v[12:15]
	v_add_f32_e32 v202, v202, v220
	global_store_dword v[232:233], v222, off offset:256
	global_store_dword v[234:235], v202, off offset:256
	s_branch .Lidx_join_s0
.Lidx_first_s0:
	s_waitcnt lgkmcnt(7)
	v_mfma_f32_16x16x32_bf16 v[0:3], v[74:77], v[172:175], 0
	v_mfma_f32_16x16x32_bf16 v[8:11], v[62:65], v[172:175], 0
	s_waitcnt lgkmcnt(6)
	v_mfma_f32_16x16x32_bf16 v[4:7], v[74:77], v[176:179], 0
	v_mfma_f32_16x16x32_bf16 v[12:15], v[62:65], v[176:179], 0
	s_waitcnt lgkmcnt(5)
	v_mfma_f32_16x16x32_bf16 v[0:3], v[50:53], v[180:183], v[0:3]
	v_mfma_f32_16x16x32_bf16 v[8:11], v[66:69], v[180:183], v[8:11]
	s_waitcnt lgkmcnt(4)
	v_mfma_f32_16x16x32_bf16 v[4:7], v[50:53], v[184:187], v[4:7]
	v_mfma_f32_16x16x32_bf16 v[12:15], v[66:69], v[184:187], v[12:15]
	s_waitcnt lgkmcnt(3)
	v_mfma_f32_16x16x32_bf16 v[0:3], v[54:57], v[188:191], v[0:3]
	v_mfma_f32_16x16x32_bf16 v[8:11], v[70:73], v[188:191], v[8:11]
	s_waitcnt lgkmcnt(2)
	v_mfma_f32_16x16x32_bf16 v[4:7], v[54:57], v[192:195], v[4:7]
	v_mfma_f32_16x16x32_bf16 v[12:15], v[70:73], v[192:195], v[12:15]
	s_waitcnt lgkmcnt(1)
	v_mfma_f32_16x16x32_bf16 v[0:3], v[58:61], v[196:199], v[0:3]
	v_mfma_f32_16x16x32_bf16 v[8:11], v[78:81], v[196:199], v[8:11]
	s_waitcnt lgkmcnt(0)
	v_mfma_f32_16x16x32_bf16 v[4:7], v[58:61], v[226:229], v[4:7]
	v_mfma_f32_16x16x32_bf16 v[12:15], v[78:81], v[226:229], v[12:15]
.Lidx_join_s0:
	v_lshl_add_u64 v[232:233], v[138:139], 0, s[16:17]
	v_lshl_add_u64 v[234:235], v[138:139], 0, s[18:19]
	v_mfma_f32_16x16x32_bf16 v[16:19], v[106:109], v[172:175], 0
	v_mfma_f32_16x16x32_bf16 v[24:27], v[94:97], v[172:175], 0
	ds_read_b128 v[172:175], v129 offset:8192
	v_mfma_f32_16x16x32_bf16 v[20:23], v[106:109], v[176:179], 0
	s_cmp_ge_u32 s22, s44
	s_cbranch_scc1 .Lidx_nostage_s0_0
	v_lshl_add_u32 v236, s22, 7, v118
	v_ashrrev_i32_e32 v237, 31, v236
	s_lshl_b32 s3, s22, 15
	v_lshlrev_b64 v[236:237], 8, v[236:237]
	s_and_b32 s3, s3, 0x8000
	v_lshl_add_u64 v[236:237], v[126:127], 0, v[236:237]
	s_add_i32 s23, s26, s3
	s_mov_b32 s3, s5
	v_lshl_add_u64 v[238:239], v[236:237], 0, s[2:3]
	s_add_i32 m0, s23, s29
	s_mov_b32 s9, s5
	global_load_lds_dwordx4 v[238:239], off

; __device__ __forceinline__ void ph_indexer(const Params& p, char* shm) {
;     ...
;           IDX_TILE(ktp * 2, pr0);
;           __builtin_amdgcn_sched_barrier(0);
;           IDX_TILE(ktp * 2 + 1, pr1);
;           __builtin_amdgcn_sched_barrier(0);
;     ...
; #pragma unroll
;           for (int q = 0; q < 2; ++q) {
;             const float mine = half ? pr1[q] : pr0[q];
;             const float send = half ? pr0[q] : pr1[q];
;             const float recv = __shfl_xor(send, 32);
;             p.SC[(rowb + wid * 2 + q) * L + st * 128 + ktp * 64 + lane] = mine + recv;
;           }
.Lidx_nostage_s0_3:
	v_max_i32_e32 v225, 0, v1
	v_fmac_f32_e32 v200, v225, v141
	v_mfma_f32_16x16x32_bf16 v[20:23], v[82:85], v[184:187], v[20:23]
	v_max_i32_e32 v224, 0, v2
	v_fmac_f32_e32 v200, v224, v142
	v_max_i32_e32 v225, 0, v3
	v_mfma_f32_16x16x32_bf16 v[28:31], v[98:101], v[184:187], v[28:31]
	ds_read_b128 v[184:187], v129 offset:10496
	v_fmac_f32_e32 v200, v225, v143
	v_max_i32_e32 v224, 0, v8
	v_fmac_f32_e32 v200, v224, v144
	v_mfma_f32_16x16x32_bf16 v[16:19], v[86:89], v[188:191], v[16:19]
	v_max_i32_e32 v225, 0, v9
	v_fmac_f32_e32 v200, v225, v145
	v_max_i32_e32 v224, 0, v10
	v_mfma_f32_16x16x32_bf16 v[24:27], v[102:105], v[188:191], v[24:27]
	ds_read_b128 v[188:191], v129 offset:12288
	v_fmac_f32_e32 v200, v224, v146
	v_max_i32_e32 v225, 0, v11
	v_fmac_f32_e32 v200, v225, v147
	v_mfma_f32_16x16x32_bf16 v[20:23], v[86:89], v[192:195], v[20:23]
	v_max_i32_e32 v224, 0, v4
	v_fma_f32 v201, v224, v140, 0
	v_max_i32_e32 v225, 0, v5
	v_mfma_f32_16x16x32_bf16 v[28:31], v[102:105], v[192:195], v[28:31]
	ds_read_b128 v[192:195], v129 offset:12544
	v_fmac_f32_e32 v201, v225, v141
	v_max_i32_e32 v224, 0, v6
	v_fmac_f32_e32 v201, v224, v142
	v_mfma_f32_16x16x32_bf16 v[16:19], v[90:93], v[196:199], v[16:19]
	v_max_i32_e32 v225, 0, v7
	v_fmac_f32_e32 v201, v225, v143
	v_max_i32_e32 v224, 0, v12
	v_mfma_f32_16x16x32_bf16 v[24:27], v[110:113], v[196:199], v[24:27]
	ds_read_b128 v[196:199], v129 offset:14336
	v_fmac_f32_e32 v201, v224, v144
	v_max_i32_e32 v225, 0, v13
	v_fmac_f32_e32 v201, v225, v145
	v_mfma_f32_16x16x32_bf16 v[20:23], v[90:93], v[226:229], v[20:23]
	v_max_i32_e32 v224, 0, v14
	v_fmac_f32_e32 v201, v224, v146
	v_mfma_f32_16x16x32_bf16 v[28:31], v[110:113], v[226:229], v[28:31]
	ds_read_b128 v[226:229], v129 offset:14592
	v_max_i32_e32 v225, 0, v15
	v_fmac_f32_e32 v201, v225, v147
	s_waitcnt lgkmcnt(7)
	v_mfma_f32_16x16x32_bf16 v[0:3], v[74:77], v[172:175], 0
	v_mfma_f32_16x16x32_bf16 v[8:11], v[62:65], v[172:175], 0
	s_waitcnt lgkmcnt(6)
	v_mfma_f32_16x16x32_bf16 v[4:7], v[74:77], v[176:179], 0
	v_mfma_f32_16x16x32_bf16 v[12:15], v[62:65], v[176:179], 0
	v_max_i32_e32 v230, 0, v16
	v_fma_f32 v202, v230, v148, 0
	s_waitcnt lgkmcnt(5)
	v_mfma_f32_16x16x32_bf16 v[0:3], v[50:53], v[180:183], v[0:3]
	v_max_i32_e32 v231, 0, v17
	v_fmac_f32_e32 v202, v231, v149
	v_mfma_f32_16x16x32_bf16 v[8:11], v[66:69], v[180:183], v[8:11]
	v_max_i32_e32 v230, 0, v18
	v_fmac_f32_e32 v202, v230, v150
	s_waitcnt lgkmcnt(4)
	v_mfma_f32_16x16x32_bf16 v[4:7], v[50:53], v[184:187], v[4:7]
	v_max_i32_e32 v231, 0, v19
	v_fmac_f32_e32 v202, v231, v151
	v_mfma_f32_16x16x32_bf16 v[12:15], v[66:69], v[184:187], v[12:15]
	v_max_i32_e32 v230, 0, v24
	v_fmac_f32_e32 v202, v230, v152
	s_waitcnt lgkmcnt(3)
	v_mfma_f32_16x16x32_bf16 v[0:3], v[54:57], v[188:191], v[0:3]
	v_max_i32_e32 v231, 0, v25
	v_fmac_f32_e32 v202, v231, v153
	v_mfma_f32_16x16x32_bf16 v[8:11], v[70:73], v[188:191], v[8:11]
	v_max_i32_e32 v230, 0, v26
	v_fmac_f32_e32 v202, v230, v154
	v_max_i32_e32 v231, 0, v27
	s_waitcnt lgkmcnt(2)
	v_mfma_f32_16x16x32_bf16 v[4:7], v[54:57], v[192:195], v[4:7]
	v_fmac_f32_e32 v202, v231, v155
	v_max_i32_e32 v230, 0, v20
	v_fma_f32 v203, v230, v148, 0
	v_mfma_f32_16x16x32_bf16 v[12:15], v[70:73], v[192:195], v[12:15]
	v_max_i32_e32 v231, 0, v21
	v_fmac_f32_e32 v203, v231, v149
	v_max_i32_e32 v230, 0, v22
	s_waitcnt lgkmcnt(1)
	v_mfma_f32_16x16x32_bf16 v[0:3], v[58:61], v[196:199], v[0:3]
	v_fmac_f32_e32 v203, v230, v150
	v_max_i32_e32 v231, 0, v23
	v_fmac_f32_e32 v203, v231, v151
	v_mfma_f32_16x16x32_bf16 v[8:11], v[78:81], v[196:199], v[8:11]
	v_max_i32_e32 v230, 0, v28
	v_fmac_f32_e32 v203, v230, v152
	v_max_i32_e32 v231, 0, v29
	s_waitcnt lgkmcnt(0)
	v_mfma_f32_16x16x32_bf16 v[4:7], v[58:61], v[226:229], v[4:7]
	v_fmac_f32_e32 v203, v231, v153
	v_max_i32_e32 v230, 0, v30
	v_fmac_f32_e32 v203, v230, v154
	v_mfma_f32_16x16x32_bf16 v[12:15], v[78:81], v[226:229], v[12:15]
	v_max_i32_e32 v231, 0, v31
	v_fmac_f32_e32 v203, v231, v155
	v_mfma_f32_16x16x32_bf16 v[16:19], v[106:109], v[172:175], 0
	v_mfma_f32_16x16x32_bf16 v[24:27], v[94:97], v[172:175], 0
	ds_read_b128 v[172:175], v129 offset:16384
	v_mfma_f32_16x16x32_bf16 v[20:23], v[106:109], v[176:179], 0
	v_mfma_f32_16x16x32_bf16 v[28:31], v[94:97], v[176:179], 0
	ds_read_b128 v[176:179], v129 offset:16640
	v_mfma_f32_16x16x32_bf16 v[16:19], v[82:85], v[180:183], v[16:19]
	v_max_i32_e32 v224, 0, v0
	v_fma_f32 v218, v224, v140, 0
	v_mfma_f32_16x16x32_bf16 v[24:27], v[98:101], v[180:183], v[24:27]
	ds_read_b128 v[180:183], v129 offset:18432
	v_max_i32_e32 v225, 0, v1
	v_fmac_f32_e32 v218, v225, v141
	v_mfma_f32_16x16x32_bf16 v[20:23], v[82:85], v[184:187], v[20:23]
	v_max_i32_e32 v224, 0, v2
	v_fmac_f32_e32 v218, v224, v142
	v_max_i32_e32 v225, 0, v3
	v_mfma_f32_16x16x32_bf16 v[28:31], v[98:101], v[184:187], v[28:31]
	ds_read_b128 v[184:187], v129 offset:18688
	v_fmac_f32_e32 v218, v225, v143
	v_max_i32_e32 v224, 0, v8
	v_fmac_f32_e32 v218, v224, v144
	v_mfma_f32_16x16x32_bf16 v[16:19], v[86:89], v[188:191], v[16:19]
	v_max_i32_e32 v225, 0, v9
	v_fmac_f32_e32 v218, v225, v145
	v_max_i32_e32 v224, 0, v10
	v_mfma_f32_16x16x32_bf16 v[24:27], v[102:105], v[188:191], v[24:27]
	ds_read_b128 v[188:191], v129 offset:20480
	v_fmac_f32_e32 v218, v224, v146
	v_max_i32_e32 v225, 0, v11
	v_fmac_f32_e32 v218, v225, v147
	v_mfma_f32_16x16x32_bf16 v[20:23], v[86:89], v[192:195], v[20:23]
	v_max_i32_e32 v224, 0, v4
	v_fma_f32 v219, v224, v140, 0
	v_max_i32_e32 v225, 0, v5
	v_mfma_f32_16x16x32_bf16 v[28:31], v[102:105], v[192:195], v[28:31]
	ds_read_b128 v[192:195], v129 offset:20736
	v_fmac_f32_e32 v219, v225, v141
	v_max_i32_e32 v224, 0, v6
	v_fmac_f32_e32 v219, v224, v142
	v_mfma_f32_16x16x32_bf16 v[16:19], v[90:93], v[196:199], v[16:19]
	v_max_i32_e32 v225, 0, v7
	v_fmac_f32_e32 v219, v225, v143
	v_max_i32_e32 v224, 0, v12
	v_mfma_f32_16x16x32_bf16 v[24:27], v[110:113], v[196:199], v[24:27]
	ds_read_b128 v[196:199], v129 offset:22528
	v_fmac_f32_e32 v219, v224, v144
	v_max_i32_e32 v225, 0, v13
	v_fmac_f32_e32 v219, v225, v145
	v_mfma_f32_16x16x32_bf16 v[20:23], v[90:93], v[226:229], v[20:23]
	v_max_i32_e32 v224, 0, v14
	v_fmac_f32_e32 v219, v224, v146
	v_mfma_f32_16x16x32_bf16 v[28:31], v[110:113], v[226:229], v[28:31]
	ds_read_b128 v[226:229], v129 offset:22784
	v_max_i32_e32 v225, 0, v15
	v_fmac_f32_e32 v219, v225, v147
	s_waitcnt lgkmcnt(7)
; __device__ __forceinline__ void ph_indexer(const Params& p, char* shm) {
;     ...
;           IDX_TILE(ktp * 2, pr0);
;           __builtin_amdgcn_sched_barrier(0);
;           IDX_TILE(ktp * 2 + 1, pr1);
;           __builtin_amdgcn_sched_barrier(0);
;     ...
; #pragma unroll
;           for (int q = 0; q < 2; ++q) {
;             const float mine = half ? pr1[q] : pr0[q];
;             const float send = half ? pr0[q] : pr1[q];
;             const float recv = __shfl_xor(send, 32);
;             p.SC[(rowb + wid * 2 + q) * L + st * 128 + ktp * 64 + lane] = mine + recv;
;           }
	v_mfma_f32_16x16x32_bf16 v[0:3], v[74:77], v[172:175], 0
	v_mfma_f32_16x16x32_bf16 v[8:11], v[62:65], v[172:175], 0
	s_waitcnt lgkmcnt(6)
	v_mfma_f32_16x16x32_bf16 v[4:7], v[74:77], v[176:179], 0
	v_mfma_f32_16x16x32_bf16 v[12:15], v[62:65], v[176:179], 0
	v_max_i32_e32 v230, 0, v16
	v_fma_f32 v220, v230, v148, 0
	s_waitcnt lgkmcnt(5)
	v_mfma_f32_16x16x32_bf16 v[0:3], v[50:53], v[180:183], v[0:3]
	v_max_i32_e32 v231, 0, v17
	v_fmac_f32_e32 v220, v231, v149
	v_mfma_f32_16x16x32_bf16 v[8:11], v[66:69], v[180:183], v[8:11]
	v_max_i32_e32 v230, 0, v18
	v_fmac_f32_e32 v220, v230, v150
	s_waitcnt lgkmcnt(4)
	v_mfma_f32_16x16x32_bf16 v[4:7], v[50:53], v[184:187], v[4:7]
	v_max_i32_e32 v231, 0, v19
	v_fmac_f32_e32 v220, v231, v151
	v_mfma_f32_16x16x32_bf16 v[12:15], v[66:69], v[184:187], v[12:15]
	v_max_i32_e32 v230, 0, v24
	v_fmac_f32_e32 v220, v230, v152
	s_waitcnt lgkmcnt(3)
	v_mfma_f32_16x16x32_bf16 v[0:3], v[54:57], v[188:191], v[0:3]
	v_max_i32_e32 v231, 0, v25
	v_fmac_f32_e32 v220, v231, v153
	v_mfma_f32_16x16x32_bf16 v[8:11], v[70:73], v[188:191], v[8:11]
	v_max_i32_e32 v230, 0, v26
	v_fmac_f32_e32 v220, v230, v154
	v_max_i32_e32 v231, 0, v27
	s_waitcnt lgkmcnt(2)
	v_mfma_f32_16x16x32_bf16 v[4:7], v[54:57], v[192:195], v[4:7]
	v_fmac_f32_e32 v220, v231, v155
	v_max_i32_e32 v230, 0, v20
	v_fma_f32 v221, v230, v148, 0
	v_mfma_f32_16x16x32_bf16 v[12:15], v[70:73], v[192:195], v[12:15]
	v_max_i32_e32 v231, 0, v21
	v_fmac_f32_e32 v221, v231, v149
	v_max_i32_e32 v230, 0, v22
	s_waitcnt lgkmcnt(1)
	v_mfma_f32_16x16x32_bf16 v[0:3], v[58:61], v[196:199], v[0:3]
	v_fmac_f32_e32 v221, v230, v150
	v_max_i32_e32 v231, 0, v23
	v_fmac_f32_e32 v221, v231, v151
	v_mfma_f32_16x16x32_bf16 v[8:11], v[78:81], v[196:199], v[8:11]
	v_max_i32_e32 v230, 0, v28
	v_fmac_f32_e32 v221, v230, v152
	v_max_i32_e32 v231, 0, v29
	s_waitcnt lgkmcnt(0)
	v_mfma_f32_16x16x32_bf16 v[4:7], v[58:61], v[226:229], v[4:7]
	v_fmac_f32_e32 v221, v231, v153
	v_max_i32_e32 v230, 0, v30
	v_fmac_f32_e32 v221, v230, v154
	v_mfma_f32_16x16x32_bf16 v[12:15], v[78:81], v[226:229], v[12:15]
	v_max_i32_e32 v231, 0, v31
	v_fmac_f32_e32 v221, v231, v155
	v_mfma_f32_16x16x32_bf16 v[16:19], v[106:109], v[172:175], 0
	s_nop 1
	v_permlane16_swap_b32_e32 v200, v201
	v_permlane16_swap_b32_e32 v218, v219
	v_permlane16_swap_b32_e32 v202, v203
	v_mfma_f32_16x16x32_bf16 v[24:27], v[94:97], v[172:175], 0
	ds_read_b128 v[172:175], v129 offset:24576
	v_permlane16_swap_b32_e32 v220, v221
	v_add_f32_e32 v200, v200, v201
	v_add_f32_e32 v218, v218, v219
	v_add_f32_e32 v202, v202, v203
	v_mfma_f32_16x16x32_bf16 v[20:23], v[106:109], v[176:179], 0
	v_add_f32_e32 v220, v220, v221
	s_nop 1
	v_permlane32_swap_b32_e32 v200, v218
	v_permlane32_swap_b32_e32 v202, v220
	v_mfma_f32_16x16x32_bf16 v[28:31], v[94:97], v[176:179], 0
	ds_read_b128 v[176:179], v129 offset:24832
	v_add_f32_e32 v200, v200, v218
	v_add_f32_e32 v202, v202, v220
	global_store_dword v[232:233], v200, off
	global_store_dword v[234:235], v202, off
	v_mfma_f32_16x16x32_bf16 v[16:19], v[82:85], v[180:183], v[16:19]
	v_max_i32_e32 v224, 0, v0
	v_fma_f32 v222, v224, v140, 0
	v_mfma_f32_16x16x32_bf16 v[24:27], v[98:101], v[180:183], v[24:27]
	ds_read_b128 v[180:183], v129 offset:26624
	v_max_i32_e32 v225, 0, v1
	v_fmac_f32_e32 v222, v225, v141
	v_mfma_f32_16x16x32_bf16 v[20:23], v[82:85], v[184:187], v[20:23]
	v_max_i32_e32 v224, 0, v2
	v_fmac_f32_e32 v222, v224, v142
	v_max_i32_e32 v225, 0, v3
	v_mfma_f32_16x16x32_bf16 v[28:31], v[98:101], v[184:187], v[28:31]
	ds_read_b128 v[184:187], v129 offset:26880
	v_fmac_f32_e32 v222, v225, v143
	v_max_i32_e32 v224, 0, v8
	v_fmac_f32_e32 v222, v224, v144
	v_mfma_f32_16x16x32_bf16 v[16:19], v[86:89], v[188:191], v[16:19]
	v_max_i32_e32 v225, 0, v9
	v_fmac_f32_e32 v222, v225, v145
	v_max_i32_e32 v224, 0, v10
	v_mfma_f32_16x16x32_bf16 v[24:27], v[102:105], v[188:191], v[24:27]
	ds_read_b128 v[188:191], v129 offset:28672
	v_fmac_f32_e32 v222, v224, v146
	v_max_i32_e32 v225, 0, v11
	v_fmac_f32_e32 v222, v225, v147
	v_mfma_f32_16x16x32_bf16 v[20:23], v[86:89], v[192:195], v[20:23]
	v_max_i32_e32 v224, 0, v4
	v_fma_f32 v223, v224, v140, 0
	v_max_i32_e32 v225, 0, v5
	v_mfma_f32_16x16x32_bf16 v[28:31], v[102:105], v[192:195], v[28:31]
	ds_read_b128 v[192:195], v129 offset:28928
	v_fmac_f32_e32 v223, v225, v141
	v_max_i32_e32 v224, 0, v6
	v_fmac_f32_e32 v223, v224, v142
	v_mfma_f32_16x16x32_bf16 v[16:19], v[90:93], v[196:199], v[16:19]
	v_max_i32_e32 v225, 0, v7
	v_fmac_f32_e32 v223, v225, v143
	v_max_i32_e32 v224, 0, v12
	v_mfma_f32_16x16x32_bf16 v[24:27], v[110:113], v[196:199], v[24:27]
	ds_read_b128 v[196:199], v129 offset:30720
	v_fmac_f32_e32 v223, v224, v144
	v_max_i32_e32 v225, 0, v13
	v_fmac_f32_e32 v223, v225, v145
	v_mfma_f32_16x16x32_bf16 v[20:23], v[90:93], v[226:229], v[20:23]
	v_max_i32_e32 v224, 0, v14
	v_fmac_f32_e32 v223, v224, v146
	v_mfma_f32_16x16x32_bf16 v[28:31], v[110:113], v[226:229], v[28:31]
	ds_read_b128 v[226:229], v129 offset:30976
	v_max_i32_e32 v225, 0, v15
	v_fmac_f32_e32 v223, v225, v147
	s_waitcnt lgkmcnt(7)
	v_mfma_f32_16x16x32_bf16 v[0:3], v[74:77], v[172:175], 0
	v_mfma_f32_16x16x32_bf16 v[8:11], v[62:65], v[172:175], 0
	s_waitcnt lgkmcnt(6)
	v_mfma_f32_16x16x32_bf16 v[4:7], v[74:77], v[176:179], 0
	v_mfma_f32_16x16x32_bf16 v[12:15], v[62:65], v[176:179], 0
	v_max_i32_e32 v230, 0, v16
	v_fma_f32 v202, v230, v148, 0
	s_waitcnt lgkmcnt(5)
; __device__ __forceinline__ void ph_indexer(const Params& p, char* shm) {
;     ...
;           IDX_TILE(ktp * 2, pr0);
;           __builtin_amdgcn_sched_barrier(0);
;           IDX_TILE(ktp * 2 + 1, pr1);
;           __builtin_amdgcn_sched_barrier(0);
;     ...
; #pragma unroll
;           for (int q = 0; q < 2; ++q) {
;             const float mine = half ? pr1[q] : pr0[q];
;             const float send = half ? pr0[q] : pr1[q];
;             const float recv = __shfl_xor(send, 32);
;             p.SC[(rowb + wid * 2 + q) * L + st * 128 + ktp * 64 + lane] = mine + recv;
;           }
	v_mfma_f32_16x16x32_bf16 v[0:3], v[50:53], v[180:183], v[0:3]
	v_max_i32_e32 v231, 0, v17
	v_fmac_f32_e32 v202, v231, v149
	v_mfma_f32_16x16x32_bf16 v[8:11], v[66:69], v[180:183], v[8:11]
	v_max_i32_e32 v230, 0, v18
	v_fmac_f32_e32 v202, v230, v150
	s_waitcnt lgkmcnt(4)
	v_mfma_f32_16x16x32_bf16 v[4:7], v[50:53], v[184:187], v[4:7]
	v_max_i32_e32 v231, 0, v19
	v_fmac_f32_e32 v202, v231, v151
	v_mfma_f32_16x16x32_bf16 v[12:15], v[66:69], v[184:187], v[12:15]
	v_max_i32_e32 v230, 0, v24
	v_fmac_f32_e32 v202, v230, v152
	s_waitcnt lgkmcnt(3)
	v_mfma_f32_16x16x32_bf16 v[0:3], v[54:57], v[188:191], v[0:3]
	v_max_i32_e32 v231, 0, v25
	v_fmac_f32_e32 v202, v231, v153
	v_mfma_f32_16x16x32_bf16 v[8:11], v[70:73], v[188:191], v[8:11]
	v_max_i32_e32 v230, 0, v26
	v_fmac_f32_e32 v202, v230, v154
	v_max_i32_e32 v231, 0, v27
	s_waitcnt lgkmcnt(2)
	v_mfma_f32_16x16x32_bf16 v[4:7], v[54:57], v[192:195], v[4:7]
	v_fmac_f32_e32 v202, v231, v155
	v_max_i32_e32 v230, 0, v20
	v_fma_f32 v203, v230, v148, 0
	v_mfma_f32_16x16x32_bf16 v[12:15], v[70:73], v[192:195], v[12:15]
	v_max_i32_e32 v231, 0, v21
	v_fmac_f32_e32 v203, v231, v149
	v_max_i32_e32 v230, 0, v22
	s_waitcnt lgkmcnt(1)
	v_mfma_f32_16x16x32_bf16 v[0:3], v[58:61], v[196:199], v[0:3]
	v_fmac_f32_e32 v203, v230, v150
	v_max_i32_e32 v231, 0, v23
	v_fmac_f32_e32 v203, v231, v151
	v_mfma_f32_16x16x32_bf16 v[8:11], v[78:81], v[196:199], v[8:11]
	v_max_i32_e32 v230, 0, v28
	v_fmac_f32_e32 v203, v230, v152
	v_max_i32_e32 v231, 0, v29
	s_waitcnt lgkmcnt(0)
	v_mfma_f32_16x16x32_bf16 v[4:7], v[58:61], v[226:229], v[4:7]
	v_fmac_f32_e32 v203, v231, v153
	v_max_i32_e32 v230, 0, v30
	v_fmac_f32_e32 v203, v230, v154
	v_mfma_f32_16x16x32_bf16 v[12:15], v[78:81], v[226:229], v[12:15]
	v_max_i32_e32 v231, 0, v31
	v_fmac_f32_e32 v203, v231, v155
	v_mfma_f32_16x16x32_bf16 v[16:19], v[106:109], v[172:175], 0
	v_mfma_f32_16x16x32_bf16 v[24:27], v[94:97], v[172:175], 0
	v_mfma_f32_16x16x32_bf16 v[20:23], v[106:109], v[176:179], 0
	v_mfma_f32_16x16x32_bf16 v[28:31], v[94:97], v[176:179], 0
	v_mfma_f32_16x16x32_bf16 v[16:19], v[82:85], v[180:183], v[16:19]
	v_max_i32_e32 v224, 0, v0
	v_fma_f32 v218, v224, v140, 0
	v_mfma_f32_16x16x32_bf16 v[24:27], v[98:101], v[180:183], v[24:27]
	v_max_i32_e32 v225, 0, v1
	v_fmac_f32_e32 v218, v225, v141
	v_mfma_f32_16x16x32_bf16 v[20:23], v[82:85], v[184:187], v[20:23]
	v_max_i32_e32 v224, 0, v2
	v_fmac_f32_e32 v218, v224, v142
	v_max_i32_e32 v225, 0, v3
	v_mfma_f32_16x16x32_bf16 v[28:31], v[98:101], v[184:187], v[28:31]
	v_fmac_f32_e32 v218, v225, v143
	v_max_i32_e32 v224, 0, v8
	v_fmac_f32_e32 v218, v224, v144
	v_mfma_f32_16x16x32_bf16 v[16:19], v[86:89], v[188:191], v[16:19]
	v_max_i32_e32 v225, 0, v9
	v_fmac_f32_e32 v218, v225, v145
	v_max_i32_e32 v224, 0, v10
	v_mfma_f32_16x16x32_bf16 v[24:27], v[102:105], v[188:191], v[24:27]
	v_fmac_f32_e32 v218, v224, v146
	v_max_i32_e32 v225, 0, v11
	v_fmac_f32_e32 v218, v225, v147
	v_mfma_f32_16x16x32_bf16 v[20:23], v[86:89], v[192:195], v[20:23]
	v_max_i32_e32 v224, 0, v4
	v_fma_f32 v219, v224, v140, 0
	v_max_i32_e32 v225, 0, v5
	v_mfma_f32_16x16x32_bf16 v[28:31], v[102:105], v[192:195], v[28:31]
	v_fmac_f32_e32 v219, v225, v141
	v_max_i32_e32 v224, 0, v6
	v_fmac_f32_e32 v219, v224, v142
	v_mfma_f32_16x16x32_bf16 v[16:19], v[90:93], v[196:199], v[16:19]
	v_max_i32_e32 v225, 0, v7
	v_fmac_f32_e32 v219, v225, v143
	v_max_i32_e32 v224, 0, v12
	v_mfma_f32_16x16x32_bf16 v[24:27], v[110:113], v[196:199], v[24:27]
	v_fmac_f32_e32 v219, v224, v144
	v_max_i32_e32 v225, 0, v13
	v_fmac_f32_e32 v219, v225, v145
	v_mfma_f32_16x16x32_bf16 v[20:23], v[90:93], v[226:229], v[20:23]
	v_max_i32_e32 v224, 0, v14
	v_fmac_f32_e32 v219, v224, v146
	v_mfma_f32_16x16x32_bf16 v[28:31], v[110:113], v[226:229], v[28:31]
	v_max_i32_e32 v225, 0, v15
	v_fmac_f32_e32 v219, v225, v147
	s_cmp_lg_u32 s22, s44
	s_cbranch_scc0 .Lidx_flush_s0
	s_mov_b32 s4, s22
	s_branch .LBB0_920
.Lidx_flush_s0:
	s_nop 7
	v_max_i32_e32 v230, 0, v16
	v_fma_f32 v220, v230, v148, 0
	v_max_i32_e32 v231, 0, v17
	v_fmac_f32_e32 v220, v231, v149
	v_max_i32_e32 v230, 0, v18
	v_fmac_f32_e32 v220, v230, v150
	v_max_i32_e32 v231, 0, v19
	v_fmac_f32_e32 v220, v231, v151
	v_max_i32_e32 v230, 0, v24
	v_fmac_f32_e32 v220, v230, v152
	v_max_i32_e32 v231, 0, v25
	v_fmac_f32_e32 v220, v231, v153
	v_max_i32_e32 v230, 0, v26
	v_fmac_f32_e32 v220, v230, v154
	v_max_i32_e32 v231, 0, v27
	v_fmac_f32_e32 v220, v231, v155
	v_max_i32_e32 v230, 0, v20
	v_fma_f32 v221, v230, v148, 0
	v_max_i32_e32 v231, 0, v21
	v_fmac_f32_e32 v221, v231, v149
	v_max_i32_e32 v230, 0, v22
	v_fmac_f32_e32 v221, v230, v150
	v_max_i32_e32 v231, 0, v23
	v_fmac_f32_e32 v221, v231, v151
	v_max_i32_e32 v230, 0, v28
	v_fmac_f32_e32 v221, v230, v152
	v_max_i32_e32 v231, 0, v29
	v_fmac_f32_e32 v221, v231, v153
	v_max_i32_e32 v230, 0, v30
	v_fmac_f32_e32 v221, v230, v154
	v_max_i32_e32 v231, 0, v31
	v_fmac_f32_e32 v221, v231, v155
	s_nop 1
	v_permlane16_swap_b32_e32 v222, v223
	v_permlane16_swap_b32_e32 v218, v219
	v_permlane16_swap_b32_e32 v202, v203
	v_permlane16_swap_b32_e32 v220, v221
	v_add_f32_e32 v222, v222, v223
	v_add_f32_e32 v218, v218, v219
	v_add_f32_e32 v202, v202, v203
	v_add_f32_e32 v220, v220, v221
	s_nop 1
	v_permlane32_swap_b32_e32 v222, v218
	v_permlane32_swap_b32_e32 v202, v220
	v_add_f32_e32 v222, v222, v218
	v_add_f32_e32 v202, v202, v220
	global_store_dword v[232:233], v222, off offset:256
	global_store_dword v[234:235], v202, off offset:256

; #define WAIT_V0() asm volatile("s_waitcnt vmcnt(0)" ::: "memory")
; #define WAIT_L0() asm volatile("s_waitcnt lgkmcnt(0)" ::: "memory")
; __device__ __forceinline__ void ph_indexer(const Params& p, char* shm) {
;     ...
;       for (int st = 0; st < nst; ++st) {
;         if (st == 0) WAIT_V0(); else asm volatile("s_waitcnt vmcnt(4)" ::: "memory");
;         WAIT_L0();
;         __builtin_amdgcn_s_barrier();
;         if (st + 1 < nst) IDX_STAGE((st + 1) & 1, st + 1);
.LBB0_935:
	s_cmp_eq_u32 s4, 0
	s_cselect_b64 s[18:19], -1, 0
	s_mov_b64 s[20:21], -1
	s_and_b64 vcc, exec, s[18:19]
	s_cbranch_vccnz .LBB0_937
	s_waitcnt vmcnt(2)
	s_mov_b64 s[20:21], 0

; __device__ __forceinline__ void ph_indexer(const Params& p, char* shm) {
;     ...
;           IDX_TILE(ktp * 2, pr0);
;           __builtin_amdgcn_sched_barrier(0);
;           IDX_TILE(ktp * 2 + 1, pr1);
;           __builtin_amdgcn_sched_barrier(0);
;     ...
; #pragma unroll
;           for (int q = 0; q < 2; ++q) {
;             const float mine = half ? pr1[q] : pr0[q];
;             const float send = half ? pr0[q] : pr1[q];
;             const float recv = __shfl_xor(send, 32);
;             p.SC[(rowb + wid * 2 + q) * L + st * 128 + ktp * 64 + lane] = mine + recv;
;           }
.LBB0_943:
	s_lshl_b32 s3, s4, 15
	s_and_b32 s3, s3, 0x8000
	s_lshl_b32 s4, s4, 7
	v_or_b32_e32 v112, s3, v117
	v_lshl_add_u64 v[110:111], s[4:5], 2, v[124:125]
	ds_read_b128 v[160:163], v112
	ds_read_b128 v[164:167], v112 offset:256
	ds_read_b128 v[168:171], v112 offset:2048
	ds_read_b128 v[172:175], v112 offset:2304
	ds_read_b128 v[176:179], v112 offset:4096
	ds_read_b128 v[106:109], v112 offset:4352
	ds_read_b128 v[102:105], v112 offset:6144
	ds_read_b128 v[98:101], v112 offset:6400
	s_waitcnt lgkmcnt(8)
	v_cvt_f32_f16_e32 v128, v34
	v_cvt_f32_f16_sdwa v129, v34 dst_sel:DWORD dst_unused:UNUSED_PAD src0_sel:WORD_1
	v_cvt_f32_f16_e32 v130, v35
	v_cvt_f32_f16_sdwa v131, v35 dst_sel:DWORD dst_unused:UNUSED_PAD src0_sel:WORD_1
	v_cvt_f32_f16_e32 v132, v36
	v_cvt_f32_f16_sdwa v133, v36 dst_sel:DWORD dst_unused:UNUSED_PAD src0_sel:WORD_1
	v_cvt_f32_f16_e32 v134, v37
	v_cvt_f32_f16_sdwa v135, v37 dst_sel:DWORD dst_unused:UNUSED_PAD src0_sel:WORD_1
	v_cvt_f32_f16_e32 v136, v38
	v_cvt_f32_f16_sdwa v137, v38 dst_sel:DWORD dst_unused:UNUSED_PAD src0_sel:WORD_1
	v_cvt_f32_f16_e32 v138, v39
	v_cvt_f32_f16_sdwa v139, v39 dst_sel:DWORD dst_unused:UNUSED_PAD src0_sel:WORD_1
	v_cvt_f32_f16_e32 v140, v40
	v_cvt_f32_f16_sdwa v141, v40 dst_sel:DWORD dst_unused:UNUSED_PAD src0_sel:WORD_1
	v_cvt_f32_f16_e32 v142, v41
	v_cvt_f32_f16_sdwa v143, v41 dst_sel:DWORD dst_unused:UNUSED_PAD src0_sel:WORD_1
	s_cmp_eq_u32 s20, 1
	s_cbranch_scc1 .Lidx_first_s1
	s_waitcnt lgkmcnt(7)
	v_mfma_f32_16x16x32_bf16 v[0:3], v[58:61], v[160:163], 0
	v_max_i32_e32 v226, 0, v184
	v_fma_f32 v220, v226, v136, 0
	v_max_i32_e32 v227, 0, v185
	v_mfma_f32_16x16x32_bf16 v[8:11], v[28:31], v[160:163], 0
	v_fmac_f32_e32 v220, v227, v137
	v_max_i32_e32 v226, 0, v186
	v_fmac_f32_e32 v220, v226, v138
	s_waitcnt lgkmcnt(6)
	v_mfma_f32_16x16x32_bf16 v[4:7], v[58:61], v[164:167], 0
	v_max_i32_e32 v227, 0, v187
	v_fmac_f32_e32 v220, v227, v139
	v_max_i32_e32 v226, 0, v192
	v_mfma_f32_16x16x32_bf16 v[12:15], v[28:31], v[164:167], 0
	v_fmac_f32_e32 v220, v226, v140
	v_max_i32_e32 v227, 0, v193
	v_fmac_f32_e32 v220, v227, v141
	s_waitcnt lgkmcnt(5)
	v_mfma_f32_16x16x32_bf16 v[0:3], v[16:19], v[168:171], v[0:3]
	v_max_i32_e32 v226, 0, v194
	v_fmac_f32_e32 v220, v226, v142
	v_max_i32_e32 v227, 0, v195
	v_mfma_f32_16x16x32_bf16 v[8:11], v[50:53], v[168:171], v[8:11]
	v_fmac_f32_e32 v220, v227, v143
	v_max_i32_e32 v226, 0, v188
	v_fma_f32 v221, v226, v136, 0
	s_waitcnt lgkmcnt(4)
	v_mfma_f32_16x16x32_bf16 v[4:7], v[16:19], v[172:175], v[4:7]
	v_max_i32_e32 v227, 0, v189
	v_fmac_f32_e32 v221, v227, v137
	v_max_i32_e32 v226, 0, v190
	v_mfma_f32_16x16x32_bf16 v[12:15], v[50:53], v[172:175], v[12:15]
	v_fmac_f32_e32 v221, v226, v138
	v_max_i32_e32 v227, 0, v191
	v_fmac_f32_e32 v221, v227, v139
	s_waitcnt lgkmcnt(3)
	v_mfma_f32_16x16x32_bf16 v[0:3], v[20:23], v[176:179], v[0:3]
	v_max_i32_e32 v226, 0, v196
	v_fmac_f32_e32 v221, v226, v140
	v_max_i32_e32 v227, 0, v197
	v_mfma_f32_16x16x32_bf16 v[8:11], v[54:57], v[176:179], v[8:11]
	v_fmac_f32_e32 v221, v227, v141
	v_max_i32_e32 v226, 0, v198
	v_fmac_f32_e32 v221, v226, v142
	s_waitcnt lgkmcnt(2)
	v_mfma_f32_16x16x32_bf16 v[4:7], v[20:23], v[106:109], v[4:7]
	v_max_i32_e32 v227, 0, v199
	v_fmac_f32_e32 v221, v227, v143
	s_nop 1
	v_mfma_f32_16x16x32_bf16 v[12:15], v[54:57], v[106:109], v[12:15]
	v_permlane16_swap_b32_e32 v222, v223
	v_permlane16_swap_b32_e32 v218, v219
	v_permlane16_swap_b32_e32 v202, v203
	s_waitcnt lgkmcnt(1)
	v_mfma_f32_16x16x32_bf16 v[0:3], v[24:27], v[102:105], v[0:3]
	v_permlane16_swap_b32_e32 v220, v221
	v_add_f32_e32 v222, v222, v223
	v_add_f32_e32 v218, v218, v219
	v_mfma_f32_16x16x32_bf16 v[8:11], v[62:65], v[102:105], v[8:11]
	v_add_f32_e32 v202, v202, v203
	v_add_f32_e32 v220, v220, v221
	s_nop 1
	s_waitcnt lgkmcnt(0)
	v_mfma_f32_16x16x32_bf16 v[4:7], v[24:27], v[98:101], v[4:7]
	v_permlane32_swap_b32_e32 v222, v218
	v_permlane32_swap_b32_e32 v202, v220
	v_add_f32_e32 v222, v222, v218
	v_mfma_f32_16x16x32_bf16 v[12:15], v[62:65], v[98:101], v[12:15]
	v_add_f32_e32 v202, v202, v220
	global_store_dword v[228:229], v222, off offset:256
	global_store_dword v[230:231], v202, off offset:256
	s_branch .Lidx_join_s1
.Lidx_first_s1:
	s_waitcnt lgkmcnt(7)
	v_mfma_f32_16x16x32_bf16 v[0:3], v[58:61], v[160:163], 0
	v_mfma_f32_16x16x32_bf16 v[8:11], v[28:31], v[160:163], 0
	s_waitcnt lgkmcnt(6)
	v_mfma_f32_16x16x32_bf16 v[4:7], v[58:61], v[164:167], 0
	v_mfma_f32_16x16x32_bf16 v[12:15], v[28:31], v[164:167], 0
	s_waitcnt lgkmcnt(5)
	v_mfma_f32_16x16x32_bf16 v[0:3], v[16:19], v[168:171], v[0:3]
	v_mfma_f32_16x16x32_bf16 v[8:11], v[50:53], v[168:171], v[8:11]
	s_waitcnt lgkmcnt(4)
	v_mfma_f32_16x16x32_bf16 v[4:7], v[16:19], v[172:175], v[4:7]
	v_mfma_f32_16x16x32_bf16 v[12:15], v[50:53], v[172:175], v[12:15]
	s_waitcnt lgkmcnt(3)
	v_mfma_f32_16x16x32_bf16 v[0:3], v[20:23], v[176:179], v[0:3]
	v_mfma_f32_16x16x32_bf16 v[8:11], v[54:57], v[176:179], v[8:11]
	s_waitcnt lgkmcnt(2)
	v_mfma_f32_16x16x32_bf16 v[4:7], v[20:23], v[106:109], v[4:7]
	v_mfma_f32_16x16x32_bf16 v[12:15], v[54:57], v[106:109], v[12:15]
	s_waitcnt lgkmcnt(1)
	v_mfma_f32_16x16x32_bf16 v[0:3], v[24:27], v[102:105], v[0:3]
	v_mfma_f32_16x16x32_bf16 v[8:11], v[62:65], v[102:105], v[8:11]
	s_waitcnt lgkmcnt(0)
	v_mfma_f32_16x16x32_bf16 v[4:7], v[24:27], v[98:101], v[4:7]
	v_mfma_f32_16x16x32_bf16 v[12:15], v[62:65], v[98:101], v[12:15]
.Lidx_join_s1:
	v_lshl_add_u64 v[228:229], v[110:111], 0, s[14:15]
	v_lshl_add_u64 v[230:231], v[110:111], 0, s[16:17]
	v_mfma_f32_16x16x32_bf16 v[184:187], v[90:93], v[160:163], 0
	v_mfma_f32_16x16x32_bf16 v[192:195], v[78:81], v[160:163], 0
	ds_read_b128 v[160:163], v112 offset:8192
	v_mfma_f32_16x16x32_bf16 v[188:191], v[90:93], v[164:167], 0
	s_cmp_ge_u32 s20, s22
	s_cbranch_scc1 .Lidx_nostage_s1_0
	v_lshl_add_u32 v236, s20, 7, v118
	v_ashrrev_i32_e32 v237, 31, v236
	s_lshl_b32 s3, s20, 15
	v_lshlrev_b64 v[236:237], 8, v[236:237]
	s_and_b32 s3, s3, 0x8000
	v_lshl_add_u64 v[236:237], v[126:127], 0, v[236:237]
	s_add_i32 s21, s26, s3
	s_mov_b32 s3, s5
	v_lshl_add_u64 v[238:239], v[236:237], 0, s[2:3]
	s_add_i32 m0, s21, s29
	s_mov_b32 s9, s5
	global_load_lds_dwordx4 v[238:239], off

; __device__ __forceinline__ void ph_indexer(const Params& p, char* shm) {
;     ...
;           IDX_TILE(ktp * 2, pr0);
;           __builtin_amdgcn_sched_barrier(0);
;           IDX_TILE(ktp * 2 + 1, pr1);
;           __builtin_amdgcn_sched_barrier(0);
;     ...
; #pragma unroll
;           for (int q = 0; q < 2; ++q) {
;             const float mine = half ? pr1[q] : pr0[q];
;             const float send = half ? pr0[q] : pr1[q];
;             const float recv = __shfl_xor(send, 32);
;             p.SC[(rowb + wid * 2 + q) * L + st * 128 + ktp * 64 + lane] = mine + recv;
;           }
.Lidx_nostage_s1_3:
	v_max_i32_e32 v225, 0, v1
	v_fmac_f32_e32 v200, v225, v129
	v_mfma_f32_16x16x32_bf16 v[188:191], v[66:69], v[172:175], v[188:191]
	v_max_i32_e32 v224, 0, v2
	v_fmac_f32_e32 v200, v224, v130
	v_max_i32_e32 v225, 0, v3
	v_mfma_f32_16x16x32_bf16 v[196:199], v[82:85], v[172:175], v[196:199]
	ds_read_b128 v[172:175], v112 offset:10496
	v_fmac_f32_e32 v200, v225, v131
	v_max_i32_e32 v224, 0, v8
	v_fmac_f32_e32 v200, v224, v132
	v_mfma_f32_16x16x32_bf16 v[184:187], v[70:73], v[176:179], v[184:187]
	v_max_i32_e32 v225, 0, v9
	v_fmac_f32_e32 v200, v225, v133
	v_max_i32_e32 v224, 0, v10
	v_mfma_f32_16x16x32_bf16 v[192:195], v[86:89], v[176:179], v[192:195]
	ds_read_b128 v[176:179], v112 offset:12288
	v_fmac_f32_e32 v200, v224, v134
	v_max_i32_e32 v225, 0, v11
	v_fmac_f32_e32 v200, v225, v135
	v_mfma_f32_16x16x32_bf16 v[188:191], v[70:73], v[106:109], v[188:191]
	v_max_i32_e32 v224, 0, v4
	v_fma_f32 v201, v224, v128, 0
	v_max_i32_e32 v225, 0, v5
	v_mfma_f32_16x16x32_bf16 v[196:199], v[86:89], v[106:109], v[196:199]
	ds_read_b128 v[106:109], v112 offset:12544
	v_fmac_f32_e32 v201, v225, v129
	v_max_i32_e32 v224, 0, v6
	v_fmac_f32_e32 v201, v224, v130
	v_mfma_f32_16x16x32_bf16 v[184:187], v[74:77], v[102:105], v[184:187]
	v_max_i32_e32 v225, 0, v7
	v_fmac_f32_e32 v201, v225, v131
	v_max_i32_e32 v224, 0, v12
	v_mfma_f32_16x16x32_bf16 v[192:195], v[94:97], v[102:105], v[192:195]
	ds_read_b128 v[102:105], v112 offset:14336
	v_fmac_f32_e32 v201, v224, v132
	v_max_i32_e32 v225, 0, v13
	v_fmac_f32_e32 v201, v225, v133
	v_mfma_f32_16x16x32_bf16 v[188:191], v[74:77], v[98:101], v[188:191]
	v_max_i32_e32 v224, 0, v14
	v_fmac_f32_e32 v201, v224, v134
	v_mfma_f32_16x16x32_bf16 v[196:199], v[94:97], v[98:101], v[196:199]
	ds_read_b128 v[98:101], v112 offset:14592
	v_max_i32_e32 v225, 0, v15
	v_fmac_f32_e32 v201, v225, v135
	s_waitcnt lgkmcnt(7)
	v_mfma_f32_16x16x32_bf16 v[0:3], v[58:61], v[160:163], 0
	v_mfma_f32_16x16x32_bf16 v[8:11], v[28:31], v[160:163], 0
	s_waitcnt lgkmcnt(6)
	v_mfma_f32_16x16x32_bf16 v[4:7], v[58:61], v[164:167], 0
	v_mfma_f32_16x16x32_bf16 v[12:15], v[28:31], v[164:167], 0
	v_max_i32_e32 v226, 0, v184
	v_fma_f32 v202, v226, v136, 0
	s_waitcnt lgkmcnt(5)
	v_mfma_f32_16x16x32_bf16 v[0:3], v[16:19], v[168:171], v[0:3]
	v_max_i32_e32 v227, 0, v185
	v_fmac_f32_e32 v202, v227, v137
	v_mfma_f32_16x16x32_bf16 v[8:11], v[50:53], v[168:171], v[8:11]
	v_max_i32_e32 v226, 0, v186
	v_fmac_f32_e32 v202, v226, v138
	s_waitcnt lgkmcnt(4)
	v_mfma_f32_16x16x32_bf16 v[4:7], v[16:19], v[172:175], v[4:7]
	v_max_i32_e32 v227, 0, v187
	v_fmac_f32_e32 v202, v227, v139
	v_mfma_f32_16x16x32_bf16 v[12:15], v[50:53], v[172:175], v[12:15]
	v_max_i32_e32 v226, 0, v192
	v_fmac_f32_e32 v202, v226, v140
	s_waitcnt lgkmcnt(3)
	v_mfma_f32_16x16x32_bf16 v[0:3], v[20:23], v[176:179], v[0:3]
	v_max_i32_e32 v227, 0, v193
	v_fmac_f32_e32 v202, v227, v141
	v_mfma_f32_16x16x32_bf16 v[8:11], v[54:57], v[176:179], v[8:11]
	v_max_i32_e32 v226, 0, v194
	v_fmac_f32_e32 v202, v226, v142
	v_max_i32_e32 v227, 0, v195
	s_waitcnt lgkmcnt(2)
	v_mfma_f32_16x16x32_bf16 v[4:7], v[20:23], v[106:109], v[4:7]
	v_fmac_f32_e32 v202, v227, v143
	v_max_i32_e32 v226, 0, v188
	v_fma_f32 v203, v226, v136, 0
	v_mfma_f32_16x16x32_bf16 v[12:15], v[54:57], v[106:109], v[12:15]
	v_max_i32_e32 v227, 0, v189
	v_fmac_f32_e32 v203, v227, v137
	v_max_i32_e32 v226, 0, v190
	s_waitcnt lgkmcnt(1)
	v_mfma_f32_16x16x32_bf16 v[0:3], v[24:27], v[102:105], v[0:3]
	v_fmac_f32_e32 v203, v226, v138
	v_max_i32_e32 v227, 0, v191
	v_fmac_f32_e32 v203, v227, v139
	v_mfma_f32_16x16x32_bf16 v[8:11], v[62:65], v[102:105], v[8:11]
	v_max_i32_e32 v226, 0, v196
	v_fmac_f32_e32 v203, v226, v140
	v_max_i32_e32 v227, 0, v197
	s_waitcnt lgkmcnt(0)
	v_mfma_f32_16x16x32_bf16 v[4:7], v[24:27], v[98:101], v[4:7]
	v_fmac_f32_e32 v203, v227, v141
	v_max_i32_e32 v226, 0, v198
	v_fmac_f32_e32 v203, v226, v142
	v_mfma_f32_16x16x32_bf16 v[12:15], v[62:65], v[98:101], v[12:15]
	v_max_i32_e32 v227, 0, v199
	v_fmac_f32_e32 v203, v227, v143
	v_mfma_f32_16x16x32_bf16 v[184:187], v[90:93], v[160:163], 0
	v_mfma_f32_16x16x32_bf16 v[192:195], v[78:81], v[160:163], 0
	ds_read_b128 v[160:163], v112 offset:16384
	v_mfma_f32_16x16x32_bf16 v[188:191], v[90:93], v[164:167], 0
	v_mfma_f32_16x16x32_bf16 v[196:199], v[78:81], v[164:167], 0
	ds_read_b128 v[164:167], v112 offset:16640
	v_mfma_f32_16x16x32_bf16 v[184:187], v[66:69], v[168:171], v[184:187]
	v_max_i32_e32 v224, 0, v0
	v_fma_f32 v218, v224, v128, 0
	v_mfma_f32_16x16x32_bf16 v[192:195], v[82:85], v[168:171], v[192:195]
	ds_read_b128 v[168:171], v112 offset:18432
	v_max_i32_e32 v225, 0, v1
	v_fmac_f32_e32 v218, v225, v129
	v_mfma_f32_16x16x32_bf16 v[188:191], v[66:69], v[172:175], v[188:191]
	v_max_i32_e32 v224, 0, v2
	v_fmac_f32_e32 v218, v224, v130
	v_max_i32_e32 v225, 0, v3
	v_mfma_f32_16x16x32_bf16 v[196:199], v[82:85], v[172:175], v[196:199]
	ds_read_b128 v[172:175], v112 offset:18688
	v_fmac_f32_e32 v218, v225, v131
	v_max_i32_e32 v224, 0, v8
	v_fmac_f32_e32 v218, v224, v132
	v_mfma_f32_16x16x32_bf16 v[184:187], v[70:73], v[176:179], v[184:187]
	v_max_i32_e32 v225, 0, v9
	v_fmac_f32_e32 v218, v225, v133
	v_max_i32_e32 v224, 0, v10
	v_mfma_f32_16x16x32_bf16 v[192:195], v[86:89], v[176:179], v[192:195]
	ds_read_b128 v[176:179], v112 offset:20480
	v_fmac_f32_e32 v218, v224, v134
	v_max_i32_e32 v225, 0, v11
	v_fmac_f32_e32 v218, v225, v135
	v_mfma_f32_16x16x32_bf16 v[188:191], v[70:73], v[106:109], v[188:191]
	v_max_i32_e32 v224, 0, v4
	v_fma_f32 v219, v224, v128, 0
	v_max_i32_e32 v225, 0, v5
	v_mfma_f32_16x16x32_bf16 v[196:199], v[86:89], v[106:109], v[196:199]
	ds_read_b128 v[106:109], v112 offset:20736
	v_fmac_f32_e32 v219, v225, v129
	v_max_i32_e32 v224, 0, v6
	v_fmac_f32_e32 v219, v224, v130
	v_mfma_f32_16x16x32_bf16 v[184:187], v[74:77], v[102:105], v[184:187]
	v_max_i32_e32 v225, 0, v7
	v_fmac_f32_e32 v219, v225, v131
	v_max_i32_e32 v224, 0, v12
	v_mfma_f32_16x16x32_bf16 v[192:195], v[94:97], v[102:105], v[192:195]
	ds_read_b128 v[102:105], v112 offset:22528
	v_fmac_f32_e32 v219, v224, v132
	v_max_i32_e32 v225, 0, v13
	v_fmac_f32_e32 v219, v225, v133
	v_mfma_f32_16x16x32_bf16 v[188:191], v[74:77], v[98:101], v[188:191]
	v_max_i32_e32 v224, 0, v14
	v_fmac_f32_e32 v219, v224, v134
	v_mfma_f32_16x16x32_bf16 v[196:199], v[94:97], v[98:101], v[196:199]
	ds_read_b128 v[98:101], v112 offset:22784
	v_max_i32_e32 v225, 0, v15
	v_fmac_f32_e32 v219, v225, v135
	s_waitcnt lgkmcnt(7)
; __device__ __forceinline__ void ph_indexer(const Params& p, char* shm) {
;     ...
;           IDX_TILE(ktp * 2, pr0);
;           __builtin_amdgcn_sched_barrier(0);
;           IDX_TILE(ktp * 2 + 1, pr1);
;           __builtin_amdgcn_sched_barrier(0);
;     ...
; #pragma unroll
;           for (int q = 0; q < 2; ++q) {
;             const float mine = half ? pr1[q] : pr0[q];
;             const float send = half ? pr0[q] : pr1[q];
;             const float recv = __shfl_xor(send, 32);
;             p.SC[(rowb + wid * 2 + q) * L + st * 128 + ktp * 64 + lane] = mine + recv;
;           }
	v_mfma_f32_16x16x32_bf16 v[0:3], v[58:61], v[160:163], 0
	v_mfma_f32_16x16x32_bf16 v[8:11], v[28:31], v[160:163], 0
	s_waitcnt lgkmcnt(6)
	v_mfma_f32_16x16x32_bf16 v[4:7], v[58:61], v[164:167], 0
	v_mfma_f32_16x16x32_bf16 v[12:15], v[28:31], v[164:167], 0
	v_max_i32_e32 v226, 0, v184
	v_fma_f32 v220, v226, v136, 0
	s_waitcnt lgkmcnt(5)
	v_mfma_f32_16x16x32_bf16 v[0:3], v[16:19], v[168:171], v[0:3]
	v_max_i32_e32 v227, 0, v185
	v_fmac_f32_e32 v220, v227, v137
	v_mfma_f32_16x16x32_bf16 v[8:11], v[50:53], v[168:171], v[8:11]
	v_max_i32_e32 v226, 0, v186
	v_fmac_f32_e32 v220, v226, v138
	s_waitcnt lgkmcnt(4)
	v_mfma_f32_16x16x32_bf16 v[4:7], v[16:19], v[172:175], v[4:7]
	v_max_i32_e32 v227, 0, v187
	v_fmac_f32_e32 v220, v227, v139
	v_mfma_f32_16x16x32_bf16 v[12:15], v[50:53], v[172:175], v[12:15]
	v_max_i32_e32 v226, 0, v192
	v_fmac_f32_e32 v220, v226, v140
	s_waitcnt lgkmcnt(3)
	v_mfma_f32_16x16x32_bf16 v[0:3], v[20:23], v[176:179], v[0:3]
	v_max_i32_e32 v227, 0, v193
	v_fmac_f32_e32 v220, v227, v141
	v_mfma_f32_16x16x32_bf16 v[8:11], v[54:57], v[176:179], v[8:11]
	v_max_i32_e32 v226, 0, v194
	v_fmac_f32_e32 v220, v226, v142
	v_max_i32_e32 v227, 0, v195
	s_waitcnt lgkmcnt(2)
	v_mfma_f32_16x16x32_bf16 v[4:7], v[20:23], v[106:109], v[4:7]
	v_fmac_f32_e32 v220, v227, v143
	v_max_i32_e32 v226, 0, v188
	v_fma_f32 v221, v226, v136, 0
	v_mfma_f32_16x16x32_bf16 v[12:15], v[54:57], v[106:109], v[12:15]
	v_max_i32_e32 v227, 0, v189
	v_fmac_f32_e32 v221, v227, v137
	v_max_i32_e32 v226, 0, v190
	s_waitcnt lgkmcnt(1)
	v_mfma_f32_16x16x32_bf16 v[0:3], v[24:27], v[102:105], v[0:3]
	v_fmac_f32_e32 v221, v226, v138
	v_max_i32_e32 v227, 0, v191
	v_fmac_f32_e32 v221, v227, v139
	v_mfma_f32_16x16x32_bf16 v[8:11], v[62:65], v[102:105], v[8:11]
	v_max_i32_e32 v226, 0, v196
	v_fmac_f32_e32 v221, v226, v140
	v_max_i32_e32 v227, 0, v197
	s_waitcnt lgkmcnt(0)
	v_mfma_f32_16x16x32_bf16 v[4:7], v[24:27], v[98:101], v[4:7]
	v_fmac_f32_e32 v221, v227, v141
	v_max_i32_e32 v226, 0, v198
	v_fmac_f32_e32 v221, v226, v142
	v_mfma_f32_16x16x32_bf16 v[12:15], v[62:65], v[98:101], v[12:15]
	v_max_i32_e32 v227, 0, v199
	v_fmac_f32_e32 v221, v227, v143
	v_mfma_f32_16x16x32_bf16 v[184:187], v[90:93], v[160:163], 0
	s_nop 1
	v_permlane16_swap_b32_e32 v200, v201
	v_permlane16_swap_b32_e32 v218, v219
	v_permlane16_swap_b32_e32 v202, v203
	v_mfma_f32_16x16x32_bf16 v[192:195], v[78:81], v[160:163], 0
	ds_read_b128 v[160:163], v112 offset:24576
	v_permlane16_swap_b32_e32 v220, v221
	v_add_f32_e32 v200, v200, v201
	v_add_f32_e32 v218, v218, v219
	v_add_f32_e32 v202, v202, v203
	v_mfma_f32_16x16x32_bf16 v[188:191], v[90:93], v[164:167], 0
	v_add_f32_e32 v220, v220, v221
	s_nop 1
	v_permlane32_swap_b32_e32 v200, v218
	v_permlane32_swap_b32_e32 v202, v220
	v_mfma_f32_16x16x32_bf16 v[196:199], v[78:81], v[164:167], 0
	ds_read_b128 v[164:167], v112 offset:24832
	v_add_f32_e32 v200, v200, v218
	v_add_f32_e32 v202, v202, v220
	global_store_dword v[228:229], v200, off
	global_store_dword v[230:231], v202, off
	v_mfma_f32_16x16x32_bf16 v[184:187], v[66:69], v[168:171], v[184:187]
	v_max_i32_e32 v224, 0, v0
	v_fma_f32 v222, v224, v128, 0
	v_mfma_f32_16x16x32_bf16 v[192:195], v[82:85], v[168:171], v[192:195]
	ds_read_b128 v[168:171], v112 offset:26624
	v_max_i32_e32 v225, 0, v1
	v_fmac_f32_e32 v222, v225, v129
	v_mfma_f32_16x16x32_bf16 v[188:191], v[66:69], v[172:175], v[188:191]
	v_max_i32_e32 v224, 0, v2
	v_fmac_f32_e32 v222, v224, v130
	v_max_i32_e32 v225, 0, v3
	v_mfma_f32_16x16x32_bf16 v[196:199], v[82:85], v[172:175], v[196:199]
	ds_read_b128 v[172:175], v112 offset:26880
	v_fmac_f32_e32 v222, v225, v131
	v_max_i32_e32 v224, 0, v8
	v_fmac_f32_e32 v222, v224, v132
	v_mfma_f32_16x16x32_bf16 v[184:187], v[70:73], v[176:179], v[184:187]
	v_max_i32_e32 v225, 0, v9
	v_fmac_f32_e32 v222, v225, v133
	v_max_i32_e32 v224, 0, v10
	v_mfma_f32_16x16x32_bf16 v[192:195], v[86:89], v[176:179], v[192:195]
	ds_read_b128 v[176:179], v112 offset:28672
	v_fmac_f32_e32 v222, v224, v134
	v_max_i32_e32 v225, 0, v11
	v_fmac_f32_e32 v222, v225, v135
	v_mfma_f32_16x16x32_bf16 v[188:191], v[70:73], v[106:109], v[188:191]
	v_max_i32_e32 v224, 0, v4
	v_fma_f32 v223, v224, v128, 0
	v_max_i32_e32 v225, 0, v5
	v_mfma_f32_16x16x32_bf16 v[196:199], v[86:89], v[106:109], v[196:199]
	ds_read_b128 v[106:109], v112 offset:28928
	v_fmac_f32_e32 v223, v225, v129
	v_max_i32_e32 v224, 0, v6
	v_fmac_f32_e32 v223, v224, v130
	v_mfma_f32_16x16x32_bf16 v[184:187], v[74:77], v[102:105], v[184:187]
	v_max_i32_e32 v225, 0, v7
	v_fmac_f32_e32 v223, v225, v131
	v_max_i32_e32 v224, 0, v12
	v_mfma_f32_16x16x32_bf16 v[192:195], v[94:97], v[102:105], v[192:195]
	ds_read_b128 v[102:105], v112 offset:30720
	v_fmac_f32_e32 v223, v224, v132
	v_max_i32_e32 v225, 0, v13
	v_fmac_f32_e32 v223, v225, v133
	v_mfma_f32_16x16x32_bf16 v[188:191], v[74:77], v[98:101], v[188:191]
	v_max_i32_e32 v224, 0, v14
	v_fmac_f32_e32 v223, v224, v134
	v_mfma_f32_16x16x32_bf16 v[196:199], v[94:97], v[98:101], v[196:199]
	ds_read_b128 v[98:101], v112 offset:30976
	v_max_i32_e32 v225, 0, v15
	v_fmac_f32_e32 v223, v225, v135
	s_waitcnt lgkmcnt(7)
	v_mfma_f32_16x16x32_bf16 v[0:3], v[58:61], v[160:163], 0
	v_mfma_f32_16x16x32_bf16 v[8:11], v[28:31], v[160:163], 0
	s_waitcnt lgkmcnt(6)
	v_mfma_f32_16x16x32_bf16 v[4:7], v[58:61], v[164:167], 0
	v_mfma_f32_16x16x32_bf16 v[12:15], v[28:31], v[164:167], 0
	v_max_i32_e32 v226, 0, v184
	v_fma_f32 v202, v226, v136, 0
	s_waitcnt lgkmcnt(5)
; __device__ __forceinline__ void ph_indexer(const Params& p, char* shm) {
;     ...
;           IDX_TILE(ktp * 2, pr0);
;           __builtin_amdgcn_sched_barrier(0);
;           IDX_TILE(ktp * 2 + 1, pr1);
;           __builtin_amdgcn_sched_barrier(0);
;     ...
; #pragma unroll
;           for (int q = 0; q < 2; ++q) {
;             const float mine = half ? pr1[q] : pr0[q];
;             const float send = half ? pr0[q] : pr1[q];
;             const float recv = __shfl_xor(send, 32);
;             p.SC[(rowb + wid * 2 + q) * L + st * 128 + ktp * 64 + lane] = mine + recv;
;           }
	v_mfma_f32_16x16x32_bf16 v[0:3], v[16:19], v[168:171], v[0:3]
	v_max_i32_e32 v227, 0, v185
	v_fmac_f32_e32 v202, v227, v137
	v_mfma_f32_16x16x32_bf16 v[8:11], v[50:53], v[168:171], v[8:11]
	v_max_i32_e32 v226, 0, v186
	v_fmac_f32_e32 v202, v226, v138
	s_waitcnt lgkmcnt(4)
	v_mfma_f32_16x16x32_bf16 v[4:7], v[16:19], v[172:175], v[4:7]
	v_max_i32_e32 v227, 0, v187
	v_fmac_f32_e32 v202, v227, v139
	v_mfma_f32_16x16x32_bf16 v[12:15], v[50:53], v[172:175], v[12:15]
	v_max_i32_e32 v226, 0, v192
	v_fmac_f32_e32 v202, v226, v140
	s_waitcnt lgkmcnt(3)
	v_mfma_f32_16x16x32_bf16 v[0:3], v[20:23], v[176:179], v[0:3]
	v_max_i32_e32 v227, 0, v193
	v_fmac_f32_e32 v202, v227, v141
	v_mfma_f32_16x16x32_bf16 v[8:11], v[54:57], v[176:179], v[8:11]
	v_max_i32_e32 v226, 0, v194
	v_fmac_f32_e32 v202, v226, v142
	v_max_i32_e32 v227, 0, v195
	s_waitcnt lgkmcnt(2)
	v_mfma_f32_16x16x32_bf16 v[4:7], v[20:23], v[106:109], v[4:7]
	v_fmac_f32_e32 v202, v227, v143
	v_max_i32_e32 v226, 0, v188
	v_fma_f32 v203, v226, v136, 0
	v_mfma_f32_16x16x32_bf16 v[12:15], v[54:57], v[106:109], v[12:15]
	v_max_i32_e32 v227, 0, v189
	v_fmac_f32_e32 v203, v227, v137
	v_max_i32_e32 v226, 0, v190
	s_waitcnt lgkmcnt(1)
	v_mfma_f32_16x16x32_bf16 v[0:3], v[24:27], v[102:105], v[0:3]
	v_fmac_f32_e32 v203, v226, v138
	v_max_i32_e32 v227, 0, v191
	v_fmac_f32_e32 v203, v227, v139
	v_mfma_f32_16x16x32_bf16 v[8:11], v[62:65], v[102:105], v[8:11]
	v_max_i32_e32 v226, 0, v196
	v_fmac_f32_e32 v203, v226, v140
	v_max_i32_e32 v227, 0, v197
	s_waitcnt lgkmcnt(0)
	v_mfma_f32_16x16x32_bf16 v[4:7], v[24:27], v[98:101], v[4:7]
	v_fmac_f32_e32 v203, v227, v141
	v_max_i32_e32 v226, 0, v198
	v_fmac_f32_e32 v203, v226, v142
	v_mfma_f32_16x16x32_bf16 v[12:15], v[62:65], v[98:101], v[12:15]
	v_max_i32_e32 v227, 0, v199
	v_fmac_f32_e32 v203, v227, v143
	v_mfma_f32_16x16x32_bf16 v[184:187], v[90:93], v[160:163], 0
	v_mfma_f32_16x16x32_bf16 v[192:195], v[78:81], v[160:163], 0
	v_mfma_f32_16x16x32_bf16 v[188:191], v[90:93], v[164:167], 0
	v_mfma_f32_16x16x32_bf16 v[196:199], v[78:81], v[164:167], 0
	v_mfma_f32_16x16x32_bf16 v[184:187], v[66:69], v[168:171], v[184:187]
	v_max_i32_e32 v224, 0, v0
	v_fma_f32 v218, v224, v128, 0
	v_mfma_f32_16x16x32_bf16 v[192:195], v[82:85], v[168:171], v[192:195]
	v_max_i32_e32 v225, 0, v1
	v_fmac_f32_e32 v218, v225, v129
	v_mfma_f32_16x16x32_bf16 v[188:191], v[66:69], v[172:175], v[188:191]
	v_max_i32_e32 v224, 0, v2
	v_fmac_f32_e32 v218, v224, v130
	v_max_i32_e32 v225, 0, v3
	v_mfma_f32_16x16x32_bf16 v[196:199], v[82:85], v[172:175], v[196:199]
	v_fmac_f32_e32 v218, v225, v131
	v_max_i32_e32 v224, 0, v8
	v_fmac_f32_e32 v218, v224, v132
	v_mfma_f32_16x16x32_bf16 v[184:187], v[70:73], v[176:179], v[184:187]
	v_max_i32_e32 v225, 0, v9
	v_fmac_f32_e32 v218, v225, v133
	v_max_i32_e32 v224, 0, v10
	v_mfma_f32_16x16x32_bf16 v[192:195], v[86:89], v[176:179], v[192:195]
	v_fmac_f32_e32 v218, v224, v134
	v_max_i32_e32 v225, 0, v11
	v_fmac_f32_e32 v218, v225, v135
	v_mfma_f32_16x16x32_bf16 v[188:191], v[70:73], v[106:109], v[188:191]
	v_max_i32_e32 v224, 0, v4
	v_fma_f32 v219, v224, v128, 0
	v_max_i32_e32 v225, 0, v5
	v_mfma_f32_16x16x32_bf16 v[196:199], v[86:89], v[106:109], v[196:199]
	v_fmac_f32_e32 v219, v225, v129
	v_max_i32_e32 v224, 0, v6
	v_fmac_f32_e32 v219, v224, v130
	v_mfma_f32_16x16x32_bf16 v[184:187], v[74:77], v[102:105], v[184:187]
	v_max_i32_e32 v225, 0, v7
	v_fmac_f32_e32 v219, v225, v131
	v_max_i32_e32 v224, 0, v12
	v_mfma_f32_16x16x32_bf16 v[192:195], v[94:97], v[102:105], v[192:195]
	v_fmac_f32_e32 v219, v224, v132
	v_max_i32_e32 v225, 0, v13
	v_fmac_f32_e32 v219, v225, v133
	v_mfma_f32_16x16x32_bf16 v[188:191], v[74:77], v[98:101], v[188:191]
	v_max_i32_e32 v224, 0, v14
	v_fmac_f32_e32 v219, v224, v134
	v_mfma_f32_16x16x32_bf16 v[196:199], v[94:97], v[98:101], v[196:199]
	v_max_i32_e32 v225, 0, v15
	v_fmac_f32_e32 v219, v225, v135
	s_cmp_lg_u32 s20, s22
	s_cbranch_scc0 .Lidx_flush_s1
	s_mov_b32 s4, s20
	s_branch .LBB0_935
.Lidx_flush_s1:
	s_nop 7
	v_max_i32_e32 v226, 0, v184
	v_fma_f32 v220, v226, v136, 0
	v_max_i32_e32 v227, 0, v185
	v_fmac_f32_e32 v220, v227, v137
	v_max_i32_e32 v226, 0, v186
	v_fmac_f32_e32 v220, v226, v138
	v_max_i32_e32 v227, 0, v187
	v_fmac_f32_e32 v220, v227, v139
	v_max_i32_e32 v226, 0, v192
	v_fmac_f32_e32 v220, v226, v140
	v_max_i32_e32 v227, 0, v193
	v_fmac_f32_e32 v220, v227, v141
	v_max_i32_e32 v226, 0, v194
	v_fmac_f32_e32 v220, v226, v142
	v_max_i32_e32 v227, 0, v195
	v_fmac_f32_e32 v220, v227, v143
	v_max_i32_e32 v226, 0, v188
	v_fma_f32 v221, v226, v136, 0
	v_max_i32_e32 v227, 0, v189
	v_fmac_f32_e32 v221, v227, v137
	v_max_i32_e32 v226, 0, v190
	v_fmac_f32_e32 v221, v226, v138
	v_max_i32_e32 v227, 0, v191
	v_fmac_f32_e32 v221, v227, v139
	v_max_i32_e32 v226, 0, v196
	v_fmac_f32_e32 v221, v226, v140
	v_max_i32_e32 v227, 0, v197
	v_fmac_f32_e32 v221, v227, v141
	v_max_i32_e32 v226, 0, v198
	v_fmac_f32_e32 v221, v226, v142
	v_max_i32_e32 v227, 0, v199
	v_fmac_f32_e32 v221, v227, v143
	s_nop 1
	v_permlane16_swap_b32_e32 v222, v223
	v_permlane16_swap_b32_e32 v218, v219
	v_permlane16_swap_b32_e32 v202, v203
	v_permlane16_swap_b32_e32 v220, v221
	v_add_f32_e32 v222, v222, v223
	v_add_f32_e32 v218, v218, v219
	v_add_f32_e32 v202, v202, v203
	v_add_f32_e32 v220, v220, v221
	s_nop 1
	v_permlane32_swap_b32_e32 v222, v218
	v_permlane32_swap_b32_e32 v202, v220
	v_add_f32_e32 v222, v222, v218
	v_add_f32_e32 v202, v202, v220
	global_store_dword v[228:229], v222, off offset:256
	global_store_dword v[230:231], v202, off offset:256
	s_branch .LBB0_916
